# P4 fused-LN epilogue: per-row-group loads (row stats + 4x16B of x) software-pipelined two iterations ahead into two spare VGPR sets, original dest regs fed by v_mov; removes 7 exposed HBM round trips
# speedup vs baseline: 1.0077x; 1.0077x over previous
;     DI void fused(pg8::f32x4 (&acc)[2][2][4][2], const pg8::Unit& u, int wr, int wc, int fr, int fq, pg8::PG8_LAS_T ldsp, int wid, int lane) const {
;     ...
;         f32x4 gi[2][2], bi[2][2];
; #pragma unroll
;         for (int bj = 0; bj < 2; ++bj) {
;             const int col = u.pn * 256 + bj * 128 + wc * 32 + 8 * fq;
;             if (MODE == 0) { gi[bj][0] = *(const f32x4*)(g_in + col); gi[bj][1] = *(const f32x4*)(g_in + col + 4); bi[bj][0] = *(const f32x4*)(b_in + col); bi[bj][1] = *(const f32x4*)(b_in + col + 4); }
;         }
; #pragma unroll
;         for (int ai = 0; ai < 2; ++ai)
; #pragma unroll
;             for (int m = 0; m < 4; ++m) {
;                 const int rt = ai * 128 + wr * 64 + m * 16 + fr, row = u.pm * 256 + rt;
;                 float sm = 0.f, sq = 0.f;
;                 float mu = 0.f, rs = 0.f;
;                 if (MODE == 0) { mu = stats[row * 2]; rs = stats[row * 2 + 1]; }
; #pragma unroll
;                 for (int bj = 0; bj < 2; ++bj) {
;                     const int col = u.pn * 256 + bj * 128 + wc * 32 + 8 * fq;
;                     const size_t idx = (size_t)row * DM + col;
;                     f32x4 v0, v1;
;                     if (MODE == 0) {
;                         const f32x4 x0 = *(const f32x4*)(x + idx), x1 = *(const f32x4*)(x + idx + 4);
;                         v0 = ((x0 - mu) * rs * gi[bj][0] + bi[bj][0]) * ALPHA + acc[ai][bj][m][0];
;                         v1 = ((x1 - mu) * rs * gi[bj][1] + bi[bj][1]) * ALPHA + acc[ai][bj][m][1];
;                     } else {
;                         const u32x4 w = *(const u32x4*)(pg + idx);
;                         const u32x4 hw = *(const u32x4*)(h1 + idx);
;                         v0 = (f32x4){bflo(hw.x), bfhi(hw.x), bflo(hw.y), bfhi(hw.y)} * ALPHA + acc[ai][bj][m][0];
;                         v1 = (f32x4){bflo(hw.z), bfhi(hw.z), bflo(hw.w), bfhi(hw.w)} * ALPHA + acc[ai][bj][m][1];
;                         v0[0] += bflo(w.x); v0[1] += bfhi(w.x); v0[2] += bflo(w.y); v0[3] += bfhi(w.y);
;                         v1[0] += bflo(w.z); v1[1] += bfhi(w.z); v1[2] += bflo(w.w); v1[3] += bfhi(w.w);
;                     }
;                     acc[ai][bj][m][0] = v0; acc[ai][bj][m][1] = v1;
; #pragma unroll
;                     for (int e = 0; e < 4; ++e) { sm += v0[e] + v1[e]; sq += v0[e] * v0[e] + v1[e] * v1[e]; }
;                 }
.LBB0_722:
	s_add_u32 s0, s80, 0x1c80000
	v_lshrrev_b32_e32 v128, 1, v162
	s_addc_u32 s1, s81, 0
	v_and_b32_e32 v128, 24, v128
	s_lshl_b32 s5, s4, 8
	v_lshl_or_b32 v128, s6, 8, v128
	v_readlane_b32 s2, v255, 35
	v_add_u32_e32 v164, s5, v196
	v_ashrrev_i32_e32 v165, 31, v164
	v_or_b32_e32 v160, s2, v128
	v_lshlrev_b32_e32 v128, 1, v164
	v_ashrrev_i32_e32 v129, 31, v128
	v_lshl_add_u64 v[128:129], v[128:129], 2, s[0:1]
	v_readlane_b32 s12, v255, 1
	s_waitcnt vmcnt(0)
	s_barrier
	v_ashrrev_i32_e32 v161, 31, v160
	v_mov_b64_e32 v[248:249], v[128:129]
	global_load_dwordx2 v[184:185], v[128:129], off
	v_lshlrev_b64 v[128:129], 12, v[164:165]
	v_readlane_b32 s13, v255, 2
	v_lshlrev_b64 v[166:167], 2, v[160:161]
	v_readlane_b32 s16, v255, 5
	v_lshl_add_u64 v[128:129], s[12:13], 0, v[128:129]
	v_lshl_add_u64 v[128:129], v[128:129], 0, v[166:167]
	v_mov_b64_e32 v[250:251], v[128:129]
	global_load_dwordx4 v[168:171], v[128:129], off
	global_load_dwordx4 v[172:175], v[128:129], off offset:16
	global_load_dwordx4 v[176:179], v[128:129], off offset:512
	global_load_dwordx4 v[180:183], v[128:129], off offset:528
	v_readlane_b32 s17, v255, 6
	v_readlane_b32 s18, v255, 7
	v_readlane_b32 s19, v255, 8
	v_lshl_add_u64 v[132:133], s[16:17], 0, v[166:167]
	v_and_b32_e32 v199, 63, v162
	v_lshl_add_u64 v[144:145], s[18:19], 0, v[166:167]
	global_load_dwordx4 v[136:139], v[144:145], off
	global_load_dwordx4 v[156:159], v[132:133], off
	global_load_dwordx4 v[140:143], v[132:133], off offset:16
	global_load_dwordx4 v[152:155], v[144:145], off offset:16
	global_load_dwordx4 v[128:131], v[144:145], off offset:512
	global_load_dwordx4 v[148:151], v[132:133], off offset:512
	s_nop 0
	global_load_dwordx4 v[132:135], v[132:133], off offset:528
	s_nop 0
	global_load_dwordx4 v[144:147], v[144:145], off offset:528
	global_load_dwordx2 v[212:213], v[248:249], off offset:128
	s_mov_b64 s[56:57], 0x10000
	v_lshl_add_u64 v[252:253], v[250:251], 0, s[56:57]
	global_load_dwordx4 v[214:217], v[252:253], off
	global_load_dwordx4 v[218:221], v[252:253], off offset:16
	global_load_dwordx4 v[222:225], v[252:253], off offset:512
	global_load_dwordx4 v[226:229], v[252:253], off offset:528
	global_load_dwordx2 v[230:231], v[248:249], off offset:256
	s_mov_b64 s[56:57], 0x20000
	v_lshl_add_u64 v[252:253], v[250:251], 0, s[56:57]
	global_load_dwordx4 v[232:235], v[252:253], off
	global_load_dwordx4 v[236:239], v[252:253], off offset:16
	global_load_dwordx4 v[240:243], v[252:253], off offset:512
	global_load_dwordx4 v[244:247], v[252:253], off offset:528
	s_mov_b32 s2, 0x3f9837f0
	v_lshlrev_b32_e32 v186, 2, v199
	v_xor_b32_e32 v200, 64, v186
	v_xor_b32_e32 v203, 0x80, v186
	v_cmp_gt_u32_e32 vcc, 16, v199
	v_readlane_b32 s14, v255, 3
	v_readlane_b32 s15, v255, 4
	v_readlane_b32 s20, v255, 9
	v_readlane_b32 s21, v255, 10
	v_readlane_b32 s22, v255, 11
	v_readlane_b32 s23, v255, 12
	v_readlane_b32 s24, v255, 13
	v_readlane_b32 s25, v255, 14
	v_readlane_b32 s26, v255, 15
	v_readlane_b32 s27, v255, 16
	s_waitcnt vmcnt(10)
	v_sub_f32_e32 v163, v169, v184
	v_sub_f32_e32 v162, v168, v184
	v_sub_f32_e32 v169, v171, v184
	v_sub_f32_e32 v168, v170, v184
	v_sub_f32_e32 v171, v173, v184
	v_sub_f32_e32 v170, v172, v184
	v_sub_f32_e32 v173, v175, v184
	v_sub_f32_e32 v172, v174, v184
	v_pk_mul_f32 v[162:163], v[184:185], v[162:163] op_sel:[1,0]
	v_pk_mul_f32 v[170:171], v[184:185], v[170:171] op_sel:[1,0]
	v_pk_mul_f32 v[168:169], v[184:185], v[168:169] op_sel:[1,0]
	v_pk_mul_f32 v[172:173], v[184:185], v[172:173] op_sel:[1,0]
	v_pk_fma_f32 v[162:163], v[156:157], v[162:163], v[136:137]
	v_pk_fma_f32 v[170:171], v[140:141], v[170:171], v[152:153]
	v_sub_f32_e32 v175, v177, v184
	v_sub_f32_e32 v174, v176, v184
	v_pk_fma_f32 v[168:169], v[158:159], v[168:169], v[138:139]
	v_pk_fma_f32 v[172:173], v[142:143], v[172:173], v[154:155]
	v_pk_fma_f32 v[124:125], v[162:163], s[2:3], v[124:125] op_sel_hi:[1,0,1]
	v_pk_fma_f32 v[120:121], v[170:171], s[2:3], v[120:121] op_sel_hi:[1,0,1]
	v_sub_f32_e32 v177, v179, v184
	v_sub_f32_e32 v176, v178, v184
	v_sub_f32_e32 v179, v181, v184
	v_sub_f32_e32 v178, v180, v184
	v_pk_mul_f32 v[174:175], v[184:185], v[174:175] op_sel:[1,0]
	v_pk_fma_f32 v[126:127], v[168:169], s[2:3], v[126:127] op_sel_hi:[1,0,1]
	v_pk_fma_f32 v[122:123], v[172:173], s[2:3], v[122:123] op_sel_hi:[1,0,1]
	v_pk_add_f32 v[168:169], v[124:125], v[120:121]
	v_pk_mul_f32 v[170:171], v[120:121], v[120:121]
	v_pk_mul_f32 v[176:177], v[184:185], v[176:177] op_sel:[1,0]
	v_pk_mul_f32 v[178:179], v[184:185], v[178:179] op_sel:[1,0]
	v_pk_fma_f32 v[174:175], v[148:149], v[174:175], v[128:129]
	v_pk_mul_f32 v[172:173], v[122:123], v[122:123]
	v_add_f32_e32 v168, 0, v168
	v_pk_fma_f32 v[170:171], v[124:125], v[124:125], v[170:171]
	v_pk_fma_f32 v[176:177], v[150:151], v[176:177], v[130:131]
	v_pk_fma_f32 v[178:179], v[132:133], v[178:179], v[144:145]
	v_pk_fma_f32 v[116:117], v[174:175], s[2:3], v[116:117] op_sel_hi:[1,0,1]
	v_pk_add_f32 v[162:163], v[126:127], v[122:123]
	v_pk_fma_f32 v[172:173], v[126:127], v[126:127], v[172:173]
	v_add_f32_e32 v168, v169, v168
	v_add_f32_e32 v169, v170, v171
	v_sub_f32_e32 v181, v183, v184
	v_sub_f32_e32 v180, v182, v184
	v_pk_fma_f32 v[118:119], v[176:177], s[2:3], v[118:119] op_sel_hi:[1,0,1]
	v_pk_fma_f32 v[112:113], v[178:179], s[2:3], v[112:113] op_sel_hi:[1,0,1]
	v_pk_mul_f32 v[176:177], v[116:117], v[116:117]
	v_add_f32_e32 v162, v162, v168
	v_add_f32_e32 v168, v172, v169
	v_pk_mul_f32 v[180:181], v[184:185], v[180:181] op_sel:[1,0]
	v_pk_add_f32 v[174:175], v[116:117], v[112:113]
	v_pk_fma_f32 v[176:177], v[112:113], v[112:113], v[176:177]
	v_add_f32_e32 v162, v163, v162
	v_add_f32_e32 v163, v173, v168
	v_pk_fma_f32 v[180:181], v[134:135], v[180:181], v[146:147]
	v_add_f32_e32 v168, v174, v162
	v_add_f32_e32 v162, v176, v163
	v_pk_fma_f32 v[114:115], v[180:181], s[2:3], v[114:115] op_sel_hi:[1,0,1]
	v_pk_add_f32 v[162:163], v[176:177], v[162:163] op_sel_hi:[1,0]
	v_mov_b32_e32 v170, v118
	v_mov_b32_e32 v171, v114
	v_mul_f32_e32 v162, v118, v118
	v_pk_fma_f32 v[170:171], v[170:171], v[170:171], v[162:163] op_sel_hi:[1,1,0]
	v_mov_b32_e32 v162, v115
	v_mov_b32_e32 v170, v119
	v_pk_add_f32 v[162:163], v[170:171], v[162:163]
	v_pk_add_f32 v[170:171], v[118:119], v[114:115]
	v_pk_mul_f32 v[172:173], v[118:119], v[118:119]
	v_add_f32_e32 v168, v175, v168
	v_mul_f32_e32 v169, v115, v115
	v_mov_b32_e32 v171, v173
	v_pk_add_f32 v[168:169], v[170:171], v[168:169]
	s_lshl_b32 s3, s85, 3
	v_pk_add_f32 v[162:163], v[168:169], v[162:163]
	ds_bpermute_b32 v168, v200, v162
	ds_bpermute_b32 v169, v200, v163
	s_add_i32 s7, s3, 0
	s_waitcnt lgkmcnt(0)
	v_pk_add_f32 v[162:163], v[162:163], v[168:169]
	ds_bpermute_b32 v168, v203, v162
	ds_bpermute_b32 v169, v203, v163
	s_and_saveexec_b64 s[10:11], vcc
	s_cbranch_execz .LBB0_724
	v_lshl_add_u32 v170, v196, 5, s7
	s_waitcnt lgkmcnt(0)
	v_pk_add_f32 v[162:163], v[162:163], v[168:169]
	ds_write_b64 v170, v[162:163]
; DI float bflo(unsigned w) { return __uint_as_float(w << 16); }
; DI float bfhi(unsigned w) { return __uint_as_float(w & 0xffff0000u); }
;     DI void fused(pg8::f32x4 (&acc)[2][2][4][2], const pg8::Unit& u, int wr, int wc, int fr, int fq, pg8::PG8_LAS_T ldsp, int wid, int lane) const {
;     ...
; #pragma unroll
;         for (int ai = 0; ai < 2; ++ai)
; #pragma unroll
;             for (int m = 0; m < 4; ++m) {
;                 const int rt = ai * 128 + wr * 64 + m * 16 + fr, row = u.pm * 256 + rt;
;                 float sm = 0.f, sq = 0.f;
;                 float mu = 0.f, rs = 0.f;
;                 if (MODE == 0) { mu = stats[row * 2]; rs = stats[row * 2 + 1]; }
; #pragma unroll
;                 for (int bj = 0; bj < 2; ++bj) {
;                     const int col = u.pn * 256 + bj * 128 + wc * 32 + 8 * fq;
;                     const size_t idx = (size_t)row * DM + col;
;                     f32x4 v0, v1;
;                     if (MODE == 0) {
;                         const f32x4 x0 = *(const f32x4*)(x + idx), x1 = *(const f32x4*)(x + idx + 4);
;                         v0 = ((x0 - mu) * rs * gi[bj][0] + bi[bj][0]) * ALPHA + acc[ai][bj][m][0];
;                         v1 = ((x1 - mu) * rs * gi[bj][1] + bi[bj][1]) * ALPHA + acc[ai][bj][m][1];
;                     } else {
;                         const u32x4 w = *(const u32x4*)(pg + idx);
;                         const u32x4 hw = *(const u32x4*)(h1 + idx);
;                         v0 = (f32x4){bflo(hw.x), bfhi(hw.x), bflo(hw.y), bfhi(hw.y)} * ALPHA + acc[ai][bj][m][0];
;                         v1 = (f32x4){bflo(hw.z), bfhi(hw.z), bflo(hw.w), bfhi(hw.w)} * ALPHA + acc[ai][bj][m][1];
;                         v0[0] += bflo(w.x); v0[1] += bfhi(w.x); v0[2] += bflo(w.y); v0[3] += bfhi(w.y);
;                         v1[0] += bflo(w.z); v1[1] += bfhi(w.z); v1[2] += bflo(w.w); v1[3] += bfhi(w.w);
;                     }
;                     acc[ai][bj][m][0] = v0; acc[ai][bj][m][1] = v1;
; #pragma unroll
;                     for (int e = 0; e < 4; ++e) { sm += v0[e] + v1[e]; sq += v0[e] * v0[e] + v1[e] * v1[e]; }
;                 }
;                 sm += shx(sm, 16, lane); sm += shx(sm, 32, lane);
;                 sq += shx(sq, 16, lane); sq += shx(sq, 32, lane);
;                 if (fq == 0) { P[(rt * 4 + wc) * 2] = sm; P[(rt * 4 + wc) * 2 + 1] = sq; }
.LBB0_724:
	s_or_b64 exec, exec, s[10:11]
	v_or_b32_e32 v197, 16, v196
	v_add_u32_e32 v162, s5, v197
	s_waitcnt lgkmcnt(1)
	v_lshlrev_b32_e32 v168, 1, v162
	s_waitcnt lgkmcnt(0)
	v_ashrrev_i32_e32 v169, 31, v168
	v_lshl_add_u64 v[168:169], v[168:169], 2, s[0:1]
	v_ashrrev_i32_e32 v163, 31, v162
	v_readlane_b32 s12, v255, 1
	s_waitcnt vmcnt(5)
	v_mov_b64_e32 v[184:185], v[212:213]
	v_lshlrev_b64 v[168:169], 12, v[162:163]
	v_readlane_b32 s13, v255, 2
	v_readlane_b32 s14, v255, 3
	v_readlane_b32 s15, v255, 4
	v_lshl_add_u64 v[168:169], s[12:13], 0, v[168:169]
	v_lshl_add_u64 v[180:181], v[160:161], 2, v[168:169]
	v_mov_b64_e32 v[168:169], v[214:215]
	v_mov_b64_e32 v[170:171], v[216:217]
	v_mov_b64_e32 v[172:173], v[218:219]
	v_mov_b64_e32 v[174:175], v[220:221]
	v_mov_b64_e32 v[176:177], v[222:223]
	v_mov_b64_e32 v[178:179], v[224:225]
	s_nop 0
	v_mov_b64_e32 v[180:181], v[226:227]
	v_mov_b64_e32 v[182:183], v[228:229]
	global_load_dwordx2 v[212:213], v[248:249], off offset:384
	s_mov_b64 s[56:57], 0x30000
	v_lshl_add_u64 v[252:253], v[250:251], 0, s[56:57]
	global_load_dwordx4 v[214:217], v[252:253], off
	global_load_dwordx4 v[218:221], v[252:253], off offset:16
	global_load_dwordx4 v[222:225], v[252:253], off offset:512
	global_load_dwordx4 v[226:229], v[252:253], off offset:528
	v_readlane_b32 s16, v255, 5
	v_readlane_b32 s17, v255, 6
	v_readlane_b32 s18, v255, 7
	v_readlane_b32 s19, v255, 8
	v_readlane_b32 s20, v255, 9
	v_readlane_b32 s21, v255, 10
	v_readlane_b32 s22, v255, 11
	v_readlane_b32 s23, v255, 12
	v_readlane_b32 s24, v255, 13
	v_readlane_b32 s25, v255, 14
	v_readlane_b32 s26, v255, 15
	v_readlane_b32 s27, v255, 16
	v_sub_f32_e32 v169, v169, v184
	v_sub_f32_e32 v168, v168, v184
	v_sub_f32_e32 v171, v171, v184
	v_sub_f32_e32 v170, v170, v184
	v_sub_f32_e32 v173, v173, v184
	v_sub_f32_e32 v172, v172, v184
	v_sub_f32_e32 v175, v175, v184
	v_sub_f32_e32 v174, v174, v184
	v_sub_f32_e32 v177, v177, v184
	v_sub_f32_e32 v176, v176, v184
	v_sub_f32_e32 v179, v179, v184
	v_sub_f32_e32 v178, v178, v184
	v_sub_f32_e32 v181, v181, v184
	v_sub_f32_e32 v180, v180, v184
	v_sub_f32_e32 v183, v183, v184
	v_sub_f32_e32 v182, v182, v184
	v_pk_mul_f32 v[170:171], v[184:185], v[170:171] op_sel:[1,0]
	v_pk_mul_f32 v[168:169], v[184:185], v[168:169] op_sel:[1,0]
	v_pk_mul_f32 v[172:173], v[184:185], v[172:173] op_sel:[1,0]
	v_pk_mul_f32 v[174:175], v[184:185], v[174:175] op_sel:[1,0]
	v_pk_mul_f32 v[178:179], v[184:185], v[178:179] op_sel:[1,0]
	v_pk_mul_f32 v[176:177], v[184:185], v[176:177] op_sel:[1,0]
	v_pk_mul_f32 v[182:183], v[184:185], v[182:183] op_sel:[1,0]
	v_pk_mul_f32 v[180:181], v[184:185], v[180:181] op_sel:[1,0]
	v_pk_fma_f32 v[184:185], v[156:157], v[168:169], v[136:137]
	v_pk_fma_f32 v[168:169], v[158:159], v[170:171], v[138:139]
	v_pk_fma_f32 v[170:171], v[140:141], v[172:173], v[152:153]
	v_pk_fma_f32 v[172:173], v[142:143], v[174:175], v[154:155]
	v_pk_fma_f32 v[168:169], v[168:169], s[2:3], v[110:111] op_sel_hi:[1,0,1]
	v_pk_fma_f32 v[110:111], v[184:185], s[2:3], v[108:109] op_sel_hi:[1,0,1]
	v_pk_fma_f32 v[104:105], v[170:171], s[2:3], v[104:105] op_sel_hi:[1,0,1]
	v_pk_fma_f32 v[174:175], v[148:149], v[176:177], v[128:129]
	v_pk_fma_f32 v[108:109], v[172:173], s[2:3], v[106:107] op_sel_hi:[1,0,1]
	v_pk_add_f32 v[170:171], v[110:111], v[104:105]
	v_pk_mul_f32 v[172:173], v[104:105], v[104:105]
	v_pk_fma_f32 v[100:101], v[174:175], s[2:3], v[100:101] op_sel_hi:[1,0,1]
	v_pk_mul_f32 v[174:175], v[108:109], v[108:109]
	v_add_f32_e32 v170, 0, v170
	v_pk_fma_f32 v[172:173], v[110:111], v[110:111], v[172:173]
	v_pk_fma_f32 v[176:177], v[150:151], v[178:179], v[130:131]
	v_pk_fma_f32 v[178:179], v[132:133], v[180:181], v[144:145]
	v_pk_add_f32 v[106:107], v[168:169], v[108:109]
	v_pk_fma_f32 v[174:175], v[168:169], v[168:169], v[174:175]
	v_add_f32_e32 v170, v171, v170
	v_add_f32_e32 v171, v172, v173
	v_pk_fma_f32 v[180:181], v[134:135], v[182:183], v[146:147]
	v_pk_fma_f32 v[96:97], v[178:179], s[2:3], v[96:97] op_sel_hi:[1,0,1]
	v_pk_mul_f32 v[178:179], v[100:101], v[100:101]
	v_add_f32_e32 v106, v106, v170
	v_add_f32_e32 v170, v174, v171
	v_pk_fma_f32 v[102:103], v[176:177], s[2:3], v[102:103] op_sel_hi:[1,0,1]
	v_pk_fma_f32 v[98:99], v[180:181], s[2:3], v[98:99] op_sel_hi:[1,0,1]
	v_pk_add_f32 v[176:177], v[100:101], v[96:97]
	v_pk_fma_f32 v[178:179], v[96:97], v[96:97], v[178:179]
	v_add_f32_e32 v106, v107, v106
	v_add_f32_e32 v107, v175, v170
	v_mov_b32_e32 v180, v102
	v_mov_b32_e32 v181, v98
	v_mul_f32_e32 v182, v102, v102
	v_mul_f32_e32 v183, v99, v99
	v_add_f32_e32 v170, v176, v106
	v_add_f32_e32 v106, v178, v107
	v_pk_add_f32 v[184:185], v[102:103], v[98:99]
	v_pk_mul_f32 v[186:187], v[102:103], v[102:103]
	v_pk_fma_f32 v[180:181], v[180:181], v[180:181], v[182:183] op_sel_hi:[1,1,0]
	v_pk_add_f32 v[106:107], v[178:179], v[106:107] op_sel_hi:[1,0]
	v_mov_b32_e32 v185, v187
	v_mov_b32_e32 v180, v103
	v_add_f32_e32 v182, v177, v170
	v_mov_b32_e32 v106, v99
	v_pk_add_f32 v[170:171], v[184:185], v[182:183]
	v_pk_add_f32 v[106:107], v[180:181], v[106:107]
	s_nop 0
	v_pk_add_f32 v[106:107], v[170:171], v[106:107]
	ds_bpermute_b32 v170, v200, v106
	ds_bpermute_b32 v171, v200, v107
	s_waitcnt lgkmcnt(0)
	v_pk_add_f32 v[106:107], v[106:107], v[170:171]
	ds_bpermute_b32 v170, v203, v106
	ds_bpermute_b32 v171, v203, v107
	s_and_saveexec_b64 s[2:3], vcc
	s_cbranch_execz .LBB0_726
	v_lshl_add_u32 v172, v197, 5, s7
	s_waitcnt lgkmcnt(0)
	v_pk_add_f32 v[106:107], v[106:107], v[170:171]
	ds_write_b64 v172, v[106:107]
; DI float bflo(unsigned w) { return __uint_as_float(w << 16); }
; DI float bfhi(unsigned w) { return __uint_as_float(w & 0xffff0000u); }
;     DI void fused(pg8::f32x4 (&acc)[2][2][4][2], const pg8::Unit& u, int wr, int wc, int fr, int fq, pg8::PG8_LAS_T ldsp, int wid, int lane) const {
;     ...
; #pragma unroll
;         for (int ai = 0; ai < 2; ++ai)
; #pragma unroll
;             for (int m = 0; m < 4; ++m) {
;                 const int rt = ai * 128 + wr * 64 + m * 16 + fr, row = u.pm * 256 + rt;
;                 float sm = 0.f, sq = 0.f;
;                 float mu = 0.f, rs = 0.f;
;                 if (MODE == 0) { mu = stats[row * 2]; rs = stats[row * 2 + 1]; }
; #pragma unroll
;                 for (int bj = 0; bj < 2; ++bj) {
;                     const int col = u.pn * 256 + bj * 128 + wc * 32 + 8 * fq;
;                     const size_t idx = (size_t)row * DM + col;
;                     f32x4 v0, v1;
;                     if (MODE == 0) {
;                         const f32x4 x0 = *(const f32x4*)(x + idx), x1 = *(const f32x4*)(x + idx + 4);
;                         v0 = ((x0 - mu) * rs * gi[bj][0] + bi[bj][0]) * ALPHA + acc[ai][bj][m][0];
;                         v1 = ((x1 - mu) * rs * gi[bj][1] + bi[bj][1]) * ALPHA + acc[ai][bj][m][1];
;                     } else {
;                         const u32x4 w = *(const u32x4*)(pg + idx);
;                         const u32x4 hw = *(const u32x4*)(h1 + idx);
;                         v0 = (f32x4){bflo(hw.x), bfhi(hw.x), bflo(hw.y), bfhi(hw.y)} * ALPHA + acc[ai][bj][m][0];
;                         v1 = (f32x4){bflo(hw.z), bfhi(hw.z), bflo(hw.w), bfhi(hw.w)} * ALPHA + acc[ai][bj][m][1];
;                         v0[0] += bflo(w.x); v0[1] += bfhi(w.x); v0[2] += bflo(w.y); v0[3] += bfhi(w.y);
;                         v1[0] += bflo(w.z); v1[1] += bfhi(w.z); v1[2] += bflo(w.w); v1[3] += bfhi(w.w);
;                     }
;                     acc[ai][bj][m][0] = v0; acc[ai][bj][m][1] = v1;
; #pragma unroll
;                     for (int e = 0; e < 4; ++e) { sm += v0[e] + v1[e]; sq += v0[e] * v0[e] + v1[e] * v1[e]; }
;                 }
;                 sm += shx(sm, 16, lane); sm += shx(sm, 32, lane);
;                 sq += shx(sq, 16, lane); sq += shx(sq, 32, lane);
;                 if (fq == 0) { P[(rt * 4 + wc) * 2] = sm; P[(rt * 4 + wc) * 2 + 1] = sq; }
.LBB0_726:
	s_or_b64 exec, exec, s[2:3]
	v_or_b32_e32 v198, 32, v196
	v_add_u32_e32 v106, s5, v198
	s_waitcnt lgkmcnt(1)
	v_lshlrev_b32_e32 v170, 1, v106
	s_waitcnt lgkmcnt(0)
	v_ashrrev_i32_e32 v171, 31, v170
	v_lshl_add_u64 v[170:171], v[170:171], 2, s[0:1]
	v_ashrrev_i32_e32 v107, 31, v106
	v_readlane_b32 s12, v255, 1
	s_waitcnt vmcnt(5)
	v_mov_b64_e32 v[186:187], v[230:231]
	v_lshlrev_b64 v[170:171], 12, v[106:107]
	v_readlane_b32 s13, v255, 2
	s_mov_b32 s2, 0x3f9837f0
	v_readlane_b32 s14, v255, 3
	v_lshl_add_u64 v[170:171], s[12:13], 0, v[170:171]
	v_lshl_add_u64 v[182:183], v[160:161], 2, v[170:171]
	v_mov_b64_e32 v[170:171], v[232:233]
	v_mov_b64_e32 v[172:173], v[234:235]
	v_mov_b64_e32 v[174:175], v[236:237]
	v_mov_b64_e32 v[176:177], v[238:239]
	v_mov_b64_e32 v[178:179], v[240:241]
	v_mov_b64_e32 v[180:181], v[242:243]
	s_nop 0
	v_mov_b64_e32 v[182:183], v[244:245]
	v_mov_b64_e32 v[184:185], v[246:247]
	global_load_dwordx2 v[230:231], v[248:249], off offset:1024
	s_mov_b64 s[56:57], 0x80000
	v_lshl_add_u64 v[252:253], v[250:251], 0, s[56:57]
	global_load_dwordx4 v[232:235], v[252:253], off
	global_load_dwordx4 v[236:239], v[252:253], off offset:16
	global_load_dwordx4 v[240:243], v[252:253], off offset:512
	global_load_dwordx4 v[244:247], v[252:253], off offset:528
	v_readlane_b32 s15, v255, 4
	v_readlane_b32 s16, v255, 5
	v_readlane_b32 s17, v255, 6
	v_readlane_b32 s18, v255, 7
	v_readlane_b32 s19, v255, 8
	v_readlane_b32 s20, v255, 9
	v_readlane_b32 s21, v255, 10
	v_readlane_b32 s22, v255, 11
	v_readlane_b32 s23, v255, 12
	v_readlane_b32 s24, v255, 13
	v_readlane_b32 s25, v255, 14
	v_readlane_b32 s26, v255, 15
	v_readlane_b32 s27, v255, 16
	v_sub_f32_e32 v171, v171, v186
	v_sub_f32_e32 v170, v170, v186
	v_sub_f32_e32 v175, v175, v186
	v_sub_f32_e32 v174, v174, v186
	v_sub_f32_e32 v173, v173, v186
	v_sub_f32_e32 v172, v172, v186
	v_sub_f32_e32 v177, v177, v186
	v_sub_f32_e32 v176, v176, v186
	v_pk_mul_f32 v[170:171], v[186:187], v[170:171] op_sel:[1,0]
	v_pk_mul_f32 v[174:175], v[186:187], v[174:175] op_sel:[1,0]
	v_pk_mul_f32 v[172:173], v[186:187], v[172:173] op_sel:[1,0]
	v_pk_mul_f32 v[176:177], v[186:187], v[176:177] op_sel:[1,0]
	v_pk_fma_f32 v[170:171], v[156:157], v[170:171], v[136:137]
	v_pk_fma_f32 v[174:175], v[140:141], v[174:175], v[152:153]
	v_sub_f32_e32 v179, v179, v186
	v_sub_f32_e32 v178, v178, v186
	v_pk_fma_f32 v[172:173], v[158:159], v[172:173], v[138:139]
	v_pk_fma_f32 v[176:177], v[142:143], v[176:177], v[154:155]
	v_pk_fma_f32 v[92:93], v[170:171], s[2:3], v[92:93] op_sel_hi:[1,0,1]
	v_pk_fma_f32 v[88:89], v[174:175], s[2:3], v[88:89] op_sel_hi:[1,0,1]
	v_sub_f32_e32 v181, v181, v186
	v_sub_f32_e32 v180, v180, v186
	v_sub_f32_e32 v183, v183, v186
	v_sub_f32_e32 v182, v182, v186
	v_pk_mul_f32 v[178:179], v[186:187], v[178:179] op_sel:[1,0]
	v_pk_fma_f32 v[94:95], v[172:173], s[2:3], v[94:95] op_sel_hi:[1,0,1]
	v_pk_fma_f32 v[90:91], v[176:177], s[2:3], v[90:91] op_sel_hi:[1,0,1]
	v_pk_add_f32 v[172:173], v[92:93], v[88:89]
	v_pk_mul_f32 v[174:175], v[88:89], v[88:89]
	v_sub_f32_e32 v185, v185, v186
	v_sub_f32_e32 v184, v184, v186
	v_pk_mul_f32 v[180:181], v[186:187], v[180:181] op_sel:[1,0]
	v_pk_mul_f32 v[182:183], v[186:187], v[182:183] op_sel:[1,0]
	v_pk_fma_f32 v[178:179], v[148:149], v[178:179], v[128:129]
	v_pk_mul_f32 v[176:177], v[90:91], v[90:91]
	v_add_f32_e32 v172, 0, v172
	v_pk_fma_f32 v[174:175], v[92:93], v[92:93], v[174:175]
	v_pk_mul_f32 v[184:185], v[186:187], v[184:185] op_sel:[1,0]
	v_pk_fma_f32 v[180:181], v[150:151], v[180:181], v[130:131]
	v_pk_fma_f32 v[182:183], v[132:133], v[182:183], v[144:145]
	v_pk_fma_f32 v[84:85], v[178:179], s[2:3], v[84:85] op_sel_hi:[1,0,1]
	v_pk_add_f32 v[170:171], v[94:95], v[90:91]
	v_pk_fma_f32 v[176:177], v[94:95], v[94:95], v[176:177]
	v_add_f32_e32 v172, v173, v172
	v_add_f32_e32 v173, v174, v175
	v_pk_fma_f32 v[184:185], v[134:135], v[184:185], v[146:147]
	v_pk_fma_f32 v[86:87], v[180:181], s[2:3], v[86:87] op_sel_hi:[1,0,1]
	v_pk_fma_f32 v[80:81], v[182:183], s[2:3], v[80:81] op_sel_hi:[1,0,1]
	v_pk_mul_f32 v[180:181], v[84:85], v[84:85]
	v_add_f32_e32 v170, v170, v172
	v_add_f32_e32 v172, v176, v173
	v_pk_fma_f32 v[82:83], v[184:185], s[2:3], v[82:83] op_sel_hi:[1,0,1]
	v_pk_add_f32 v[178:179], v[84:85], v[80:81]
	v_pk_fma_f32 v[180:181], v[80:81], v[80:81], v[180:181]
	v_add_f32_e32 v170, v171, v170
	v_add_f32_e32 v171, v177, v172
	v_mov_b32_e32 v182, v86
	v_mov_b32_e32 v183, v82
	v_mul_f32_e32 v184, v86, v86
	v_mul_f32_e32 v185, v83, v83
	v_add_f32_e32 v172, v178, v170
	v_add_f32_e32 v170, v180, v171
	v_pk_add_f32 v[186:187], v[86:87], v[82:83]
	v_pk_mul_f32 v[188:189], v[86:87], v[86:87]
	v_pk_fma_f32 v[182:183], v[182:183], v[182:183], v[184:185] op_sel_hi:[1,1,0]
	v_pk_add_f32 v[170:171], v[180:181], v[170:171] op_sel_hi:[1,0]
	v_mov_b32_e32 v187, v189
	v_mov_b32_e32 v182, v87
	v_add_f32_e32 v184, v179, v172
	v_mov_b32_e32 v170, v83
	v_pk_add_f32 v[172:173], v[186:187], v[184:185]
	v_pk_add_f32 v[170:171], v[182:183], v[170:171]
	s_nop 0
	v_pk_add_f32 v[170:171], v[172:173], v[170:171]
	ds_bpermute_b32 v172, v200, v170
	ds_bpermute_b32 v173, v200, v171
	s_waitcnt lgkmcnt(0)
	v_pk_add_f32 v[170:171], v[170:171], v[172:173]
	ds_bpermute_b32 v172, v203, v170
	ds_bpermute_b32 v173, v203, v171
	s_and_saveexec_b64 s[10:11], vcc
	s_cbranch_execz .LBB0_728
	v_lshl_add_u32 v174, v198, 5, s7
	s_waitcnt lgkmcnt(0)
	v_pk_add_f32 v[170:171], v[170:171], v[172:173]
	ds_write_b64 v174, v[170:171]
; DI float bflo(unsigned w) { return __uint_as_float(w << 16); }
; DI float bfhi(unsigned w) { return __uint_as_float(w & 0xffff0000u); }
;     DI void fused(pg8::f32x4 (&acc)[2][2][4][2], const pg8::Unit& u, int wr, int wc, int fr, int fq, pg8::PG8_LAS_T ldsp, int wid, int lane) const {
;     ...
; #pragma unroll
;         for (int ai = 0; ai < 2; ++ai)
; #pragma unroll
;             for (int m = 0; m < 4; ++m) {
;                 const int rt = ai * 128 + wr * 64 + m * 16 + fr, row = u.pm * 256 + rt;
;                 float sm = 0.f, sq = 0.f;
;                 float mu = 0.f, rs = 0.f;
;                 if (MODE == 0) { mu = stats[row * 2]; rs = stats[row * 2 + 1]; }
; #pragma unroll
;                 for (int bj = 0; bj < 2; ++bj) {
;                     const int col = u.pn * 256 + bj * 128 + wc * 32 + 8 * fq;
;                     const size_t idx = (size_t)row * DM + col;
;                     f32x4 v0, v1;
;                     if (MODE == 0) {
;                         const f32x4 x0 = *(const f32x4*)(x + idx), x1 = *(const f32x4*)(x + idx + 4);
;                         v0 = ((x0 - mu) * rs * gi[bj][0] + bi[bj][0]) * ALPHA + acc[ai][bj][m][0];
;                         v1 = ((x1 - mu) * rs * gi[bj][1] + bi[bj][1]) * ALPHA + acc[ai][bj][m][1];
;                     } else {
;                         const u32x4 w = *(const u32x4*)(pg + idx);
;                         const u32x4 hw = *(const u32x4*)(h1 + idx);
;                         v0 = (f32x4){bflo(hw.x), bfhi(hw.x), bflo(hw.y), bfhi(hw.y)} * ALPHA + acc[ai][bj][m][0];
;                         v1 = (f32x4){bflo(hw.z), bfhi(hw.z), bflo(hw.w), bfhi(hw.w)} * ALPHA + acc[ai][bj][m][1];
;                         v0[0] += bflo(w.x); v0[1] += bfhi(w.x); v0[2] += bflo(w.y); v0[3] += bfhi(w.y);
;                         v1[0] += bflo(w.z); v1[1] += bfhi(w.z); v1[2] += bflo(w.w); v1[3] += bfhi(w.w);
;                     }
;                     acc[ai][bj][m][0] = v0; acc[ai][bj][m][1] = v1;
; #pragma unroll
;                     for (int e = 0; e < 4; ++e) { sm += v0[e] + v1[e]; sq += v0[e] * v0[e] + v1[e] * v1[e]; }
;                 }
;                 sm += shx(sm, 16, lane); sm += shx(sm, 32, lane);
;                 sq += shx(sq, 16, lane); sq += shx(sq, 32, lane);
;                 if (fq == 0) { P[(rt * 4 + wc) * 2] = sm; P[(rt * 4 + wc) * 2 + 1] = sq; }
.LBB0_728:
	s_or_b64 exec, exec, s[10:11]
	v_or_b32_e32 v201, 48, v196
	v_add_u32_e32 v170, s5, v201
	s_waitcnt lgkmcnt(1)
	v_lshlrev_b32_e32 v172, 1, v170
	s_waitcnt lgkmcnt(0)
	v_ashrrev_i32_e32 v173, 31, v172
	v_lshl_add_u64 v[172:173], v[172:173], 2, s[0:1]
	v_ashrrev_i32_e32 v171, 31, v170
	v_readlane_b32 s12, v255, 1
	s_waitcnt vmcnt(5)
	v_mov_b64_e32 v[188:189], v[212:213]
	v_lshlrev_b64 v[172:173], 12, v[170:171]
	v_readlane_b32 s13, v255, 2
	v_readlane_b32 s14, v255, 3
	v_readlane_b32 s15, v255, 4
	v_lshl_add_u64 v[172:173], s[12:13], 0, v[172:173]
	v_lshl_add_u64 v[184:185], v[160:161], 2, v[172:173]
	v_mov_b64_e32 v[172:173], v[214:215]
	v_mov_b64_e32 v[174:175], v[216:217]
	v_mov_b64_e32 v[176:177], v[218:219]
	v_mov_b64_e32 v[178:179], v[220:221]
	v_mov_b64_e32 v[180:181], v[222:223]
	v_mov_b64_e32 v[182:183], v[224:225]
	s_nop 0
	v_mov_b64_e32 v[184:185], v[226:227]
	v_mov_b64_e32 v[186:187], v[228:229]
	global_load_dwordx2 v[212:213], v[248:249], off offset:1152
	s_mov_b64 s[56:57], 0x90000
	v_lshl_add_u64 v[252:253], v[250:251], 0, s[56:57]
	global_load_dwordx4 v[214:217], v[252:253], off
	global_load_dwordx4 v[218:221], v[252:253], off offset:16
	global_load_dwordx4 v[222:225], v[252:253], off offset:512
	global_load_dwordx4 v[226:229], v[252:253], off offset:528
	v_readlane_b32 s16, v255, 5
	v_readlane_b32 s17, v255, 6
	v_readlane_b32 s18, v255, 7
	v_readlane_b32 s19, v255, 8
	v_readlane_b32 s20, v255, 9
	v_readlane_b32 s21, v255, 10
	v_readlane_b32 s22, v255, 11
	v_readlane_b32 s23, v255, 12
	v_readlane_b32 s24, v255, 13
	v_readlane_b32 s25, v255, 14
	v_readlane_b32 s26, v255, 15
	v_readlane_b32 s27, v255, 16
	v_sub_f32_e32 v173, v173, v188
	v_sub_f32_e32 v172, v172, v188
	v_sub_f32_e32 v177, v177, v188
	v_sub_f32_e32 v176, v176, v188
	v_sub_f32_e32 v175, v175, v188
	v_sub_f32_e32 v174, v174, v188
	v_sub_f32_e32 v179, v179, v188
	v_sub_f32_e32 v178, v178, v188
	v_pk_mul_f32 v[172:173], v[188:189], v[172:173] op_sel:[1,0]
	v_pk_mul_f32 v[176:177], v[188:189], v[176:177] op_sel:[1,0]
	v_pk_mul_f32 v[174:175], v[188:189], v[174:175] op_sel:[1,0]
	v_pk_mul_f32 v[178:179], v[188:189], v[178:179] op_sel:[1,0]
	v_pk_fma_f32 v[172:173], v[156:157], v[172:173], v[136:137]
	v_pk_fma_f32 v[176:177], v[140:141], v[176:177], v[152:153]
	v_sub_f32_e32 v181, v181, v188
	v_sub_f32_e32 v180, v180, v188
	v_sub_f32_e32 v183, v183, v188
	v_sub_f32_e32 v182, v182, v188
	v_sub_f32_e32 v185, v185, v188
	v_sub_f32_e32 v184, v184, v188
	v_pk_fma_f32 v[174:175], v[158:159], v[174:175], v[138:139]
	v_pk_fma_f32 v[178:179], v[142:143], v[178:179], v[154:155]
	v_pk_fma_f32 v[172:173], v[172:173], s[2:3], v[76:77] op_sel_hi:[1,0,1]
	v_pk_fma_f32 v[76:77], v[176:177], s[2:3], v[72:73] op_sel_hi:[1,0,1]
	v_pk_mul_f32 v[182:183], v[188:189], v[182:183] op_sel:[1,0]
	v_pk_mul_f32 v[180:181], v[188:189], v[180:181] op_sel:[1,0]
	v_pk_mul_f32 v[184:185], v[188:189], v[184:185] op_sel:[1,0]
	v_pk_fma_f32 v[174:175], v[174:175], s[2:3], v[78:79] op_sel_hi:[1,0,1]
	v_pk_fma_f32 v[78:79], v[178:179], s[2:3], v[74:75] op_sel_hi:[1,0,1]
	v_pk_add_f32 v[74:75], v[172:173], v[76:77]
	v_pk_mul_f32 v[176:177], v[76:77], v[76:77]
	v_sub_f32_e32 v187, v187, v188
	v_sub_f32_e32 v186, v186, v188
	v_pk_fma_f32 v[180:181], v[148:149], v[180:181], v[128:129]
	v_pk_fma_f32 v[182:183], v[150:151], v[182:183], v[130:131]
	v_pk_fma_f32 v[184:185], v[132:133], v[184:185], v[144:145]
	v_pk_mul_f32 v[178:179], v[78:79], v[78:79]
	v_add_f32_e32 v74, 0, v74
	v_pk_fma_f32 v[176:177], v[172:173], v[172:173], v[176:177]
	v_pk_mul_f32 v[186:187], v[188:189], v[186:187] op_sel:[1,0]
	v_pk_fma_f32 v[72:73], v[182:183], s[2:3], v[70:71] op_sel_hi:[1,0,1]
	v_pk_fma_f32 v[70:71], v[180:181], s[2:3], v[68:69] op_sel_hi:[1,0,1]
	v_pk_fma_f32 v[68:69], v[184:185], s[2:3], v[64:65] op_sel_hi:[1,0,1]
	v_pk_add_f32 v[64:65], v[174:175], v[78:79]
	v_pk_fma_f32 v[178:179], v[174:175], v[174:175], v[178:179]
	v_add_f32_e32 v74, v75, v74
	v_add_f32_e32 v75, v176, v177
	v_pk_fma_f32 v[186:187], v[134:135], v[186:187], v[146:147]
	v_pk_mul_f32 v[182:183], v[70:71], v[70:71]
	v_add_f32_e32 v64, v64, v74
	v_add_f32_e32 v74, v178, v75
	v_pk_fma_f32 v[66:67], v[186:187], s[2:3], v[66:67] op_sel_hi:[1,0,1]
	v_pk_add_f32 v[180:181], v[70:71], v[68:69]
	v_pk_fma_f32 v[182:183], v[68:69], v[68:69], v[182:183]
	v_add_f32_e32 v64, v65, v64
	v_add_f32_e32 v65, v179, v74
	v_mov_b32_e32 v184, v72
	v_mov_b32_e32 v185, v66
	v_mul_f32_e32 v186, v72, v72
	v_mul_f32_e32 v187, v67, v67
	v_add_f32_e32 v74, v180, v64
	v_add_f32_e32 v64, v182, v65
	v_pk_add_f32 v[188:189], v[72:73], v[66:67]
	v_pk_mul_f32 v[190:191], v[72:73], v[72:73]
	v_pk_fma_f32 v[184:185], v[184:185], v[184:185], v[186:187] op_sel_hi:[1,1,0]
	v_pk_add_f32 v[64:65], v[182:183], v[64:65] op_sel_hi:[1,0]
	v_mov_b32_e32 v189, v191
	v_mov_b32_e32 v184, v73
	v_add_f32_e32 v186, v181, v74
	v_mov_b32_e32 v64, v67
	v_pk_add_f32 v[74:75], v[188:189], v[186:187]
	v_pk_add_f32 v[64:65], v[184:185], v[64:65]
	s_nop 0
	v_pk_add_f32 v[64:65], v[74:75], v[64:65]
	ds_bpermute_b32 v74, v200, v64
	ds_bpermute_b32 v75, v200, v65
	s_waitcnt lgkmcnt(0)
	v_pk_add_f32 v[64:65], v[64:65], v[74:75]
	ds_bpermute_b32 v74, v203, v64
	ds_bpermute_b32 v75, v203, v65
	s_and_saveexec_b64 s[2:3], vcc
	s_cbranch_execz .LBB0_730
	v_lshl_add_u32 v176, v201, 5, s7
	s_waitcnt lgkmcnt(0)
	v_pk_add_f32 v[64:65], v[64:65], v[74:75]
	ds_write_b64 v176, v[64:65]
; DI float bflo(unsigned w) { return __uint_as_float(w << 16); }
; DI float bfhi(unsigned w) { return __uint_as_float(w & 0xffff0000u); }
;     DI void fused(pg8::f32x4 (&acc)[2][2][4][2], const pg8::Unit& u, int wr, int wc, int fr, int fq, pg8::PG8_LAS_T ldsp, int wid, int lane) const {
;     ...
; #pragma unroll
;         for (int ai = 0; ai < 2; ++ai)
; #pragma unroll
;             for (int m = 0; m < 4; ++m) {
;                 const int rt = ai * 128 + wr * 64 + m * 16 + fr, row = u.pm * 256 + rt;
;                 float sm = 0.f, sq = 0.f;
;                 float mu = 0.f, rs = 0.f;
;                 if (MODE == 0) { mu = stats[row * 2]; rs = stats[row * 2 + 1]; }
; #pragma unroll
;                 for (int bj = 0; bj < 2; ++bj) {
;                     const int col = u.pn * 256 + bj * 128 + wc * 32 + 8 * fq;
;                     const size_t idx = (size_t)row * DM + col;
;                     f32x4 v0, v1;
;                     if (MODE == 0) {
;                         const f32x4 x0 = *(const f32x4*)(x + idx), x1 = *(const f32x4*)(x + idx + 4);
;                         v0 = ((x0 - mu) * rs * gi[bj][0] + bi[bj][0]) * ALPHA + acc[ai][bj][m][0];
;                         v1 = ((x1 - mu) * rs * gi[bj][1] + bi[bj][1]) * ALPHA + acc[ai][bj][m][1];
;                     } else {
;                         const u32x4 w = *(const u32x4*)(pg + idx);
;                         const u32x4 hw = *(const u32x4*)(h1 + idx);
;                         v0 = (f32x4){bflo(hw.x), bfhi(hw.x), bflo(hw.y), bfhi(hw.y)} * ALPHA + acc[ai][bj][m][0];
;                         v1 = (f32x4){bflo(hw.z), bfhi(hw.z), bflo(hw.w), bfhi(hw.w)} * ALPHA + acc[ai][bj][m][1];
;                         v0[0] += bflo(w.x); v0[1] += bfhi(w.x); v0[2] += bflo(w.y); v0[3] += bfhi(w.y);
;                         v1[0] += bflo(w.z); v1[1] += bfhi(w.z); v1[2] += bflo(w.w); v1[3] += bfhi(w.w);
;                     }
;                     acc[ai][bj][m][0] = v0; acc[ai][bj][m][1] = v1;
; #pragma unroll
;                     for (int e = 0; e < 4; ++e) { sm += v0[e] + v1[e]; sq += v0[e] * v0[e] + v1[e] * v1[e]; }
;                 }
;                 sm += shx(sm, 16, lane); sm += shx(sm, 32, lane);
;                 sq += shx(sq, 16, lane); sq += shx(sq, 32, lane);
;                 if (fq == 0) { P[(rt * 4 + wc) * 2] = sm; P[(rt * 4 + wc) * 2 + 1] = sq; }
.LBB0_730:
	s_or_b64 exec, exec, s[2:3]
	v_add_u32_e32 v202, 0x80, v196
	v_add_u32_e32 v64, s5, v202
	s_waitcnt lgkmcnt(1)
	v_lshlrev_b32_e32 v74, 1, v64
	s_waitcnt lgkmcnt(0)
	v_ashrrev_i32_e32 v75, 31, v74
	v_ashrrev_i32_e32 v65, 31, v64
	v_readlane_b32 s12, v255, 1
	v_lshl_add_u64 v[74:75], v[74:75], 2, s[0:1]
	v_lshlrev_b64 v[176:177], 12, v[64:65]
	v_readlane_b32 s13, v255, 2
	s_waitcnt vmcnt(5)
	v_mov_b64_e32 v[74:75], v[230:231]
	s_mov_b32 s2, 0x3f9837f0
	v_lshl_add_u64 v[176:177], s[12:13], 0, v[176:177]
	v_lshl_add_u64 v[188:189], v[160:161], 2, v[176:177]
	v_mov_b64_e32 v[176:177], v[232:233]
	v_mov_b64_e32 v[178:179], v[234:235]
	v_mov_b64_e32 v[180:181], v[236:237]
	v_mov_b64_e32 v[182:183], v[238:239]
	v_mov_b64_e32 v[184:185], v[240:241]
	v_mov_b64_e32 v[186:187], v[242:243]
	s_nop 0
	v_mov_b64_e32 v[188:189], v[244:245]
	v_mov_b64_e32 v[190:191], v[246:247]
	global_load_dwordx2 v[230:231], v[248:249], off offset:1280
	s_mov_b64 s[56:57], 0xa0000
	v_lshl_add_u64 v[252:253], v[250:251], 0, s[56:57]
	global_load_dwordx4 v[232:235], v[252:253], off
	global_load_dwordx4 v[236:239], v[252:253], off offset:16
	global_load_dwordx4 v[240:243], v[252:253], off offset:512
	global_load_dwordx4 v[244:247], v[252:253], off offset:528
	v_readlane_b32 s14, v255, 3
	v_readlane_b32 s15, v255, 4
	v_readlane_b32 s16, v255, 5
	v_readlane_b32 s17, v255, 6
	v_readlane_b32 s18, v255, 7
	v_readlane_b32 s19, v255, 8
	v_readlane_b32 s20, v255, 9
	v_readlane_b32 s21, v255, 10
	v_readlane_b32 s22, v255, 11
	v_readlane_b32 s23, v255, 12
	v_readlane_b32 s24, v255, 13
	v_readlane_b32 s25, v255, 14
	v_readlane_b32 s26, v255, 15
	v_readlane_b32 s27, v255, 16
	v_sub_f32_e32 v177, v177, v74
	v_sub_f32_e32 v176, v176, v74
	v_sub_f32_e32 v181, v181, v74
	v_sub_f32_e32 v180, v180, v74
	v_sub_f32_e32 v179, v179, v74
	v_sub_f32_e32 v178, v178, v74
	v_sub_f32_e32 v183, v183, v74
	v_sub_f32_e32 v182, v182, v74
	v_pk_mul_f32 v[176:177], v[74:75], v[176:177] op_sel:[1,0]
	v_pk_mul_f32 v[180:181], v[74:75], v[180:181] op_sel:[1,0]
	v_pk_mul_f32 v[178:179], v[74:75], v[178:179] op_sel:[1,0]
	v_pk_mul_f32 v[182:183], v[74:75], v[182:183] op_sel:[1,0]
	v_pk_fma_f32 v[176:177], v[156:157], v[176:177], v[136:137]
	v_pk_fma_f32 v[180:181], v[140:141], v[180:181], v[152:153]
	v_sub_f32_e32 v185, v185, v74
	v_sub_f32_e32 v184, v184, v74
	v_sub_f32_e32 v187, v187, v74
	v_sub_f32_e32 v186, v186, v74
	v_sub_f32_e32 v189, v189, v74
	v_sub_f32_e32 v188, v188, v74
	v_sub_f32_e32 v191, v191, v74
	v_sub_f32_e32 v190, v190, v74
	v_pk_fma_f32 v[178:179], v[158:159], v[178:179], v[138:139]
	v_pk_fma_f32 v[182:183], v[142:143], v[182:183], v[154:155]
	v_pk_fma_f32 v[60:61], v[176:177], s[2:3], v[60:61] op_sel_hi:[1,0,1]
	v_pk_fma_f32 v[56:57], v[180:181], s[2:3], v[56:57] op_sel_hi:[1,0,1]
	v_pk_mul_f32 v[186:187], v[74:75], v[186:187] op_sel:[1,0]
	v_pk_mul_f32 v[184:185], v[74:75], v[184:185] op_sel:[1,0]
	v_pk_mul_f32 v[190:191], v[74:75], v[190:191] op_sel:[1,0]
	v_pk_mul_f32 v[74:75], v[74:75], v[188:189] op_sel:[1,0]
	v_pk_fma_f32 v[62:63], v[178:179], s[2:3], v[62:63] op_sel_hi:[1,0,1]
	v_pk_fma_f32 v[58:59], v[182:183], s[2:3], v[58:59] op_sel_hi:[1,0,1]
	v_pk_add_f32 v[176:177], v[60:61], v[56:57]
	v_pk_mul_f32 v[178:179], v[56:57], v[56:57]
	v_pk_fma_f32 v[184:185], v[148:149], v[184:185], v[128:129]
	v_pk_fma_f32 v[74:75], v[132:133], v[74:75], v[144:145]
	v_pk_mul_f32 v[180:181], v[58:59], v[58:59]
	v_add_f32_e32 v176, 0, v176
	v_pk_fma_f32 v[178:179], v[60:61], v[60:61], v[178:179]
	v_pk_fma_f32 v[52:53], v[184:185], s[2:3], v[52:53] op_sel_hi:[1,0,1]
	v_pk_fma_f32 v[48:49], v[74:75], s[2:3], v[48:49] op_sel_hi:[1,0,1]
	v_pk_add_f32 v[74:75], v[62:63], v[58:59]
	v_pk_fma_f32 v[180:181], v[62:63], v[62:63], v[180:181]
	v_add_f32_e32 v176, v177, v176
	v_add_f32_e32 v177, v178, v179
	v_pk_fma_f32 v[186:187], v[150:151], v[186:187], v[130:131]
	v_pk_fma_f32 v[188:189], v[134:135], v[190:191], v[146:147]
	v_pk_mul_f32 v[184:185], v[52:53], v[52:53]
	v_add_f32_e32 v74, v74, v176
	v_add_f32_e32 v176, v180, v177
	v_pk_fma_f32 v[54:55], v[186:187], s[2:3], v[54:55] op_sel_hi:[1,0,1]
	v_pk_fma_f32 v[50:51], v[188:189], s[2:3], v[50:51] op_sel_hi:[1,0,1]
	v_pk_add_f32 v[182:183], v[52:53], v[48:49]
	v_pk_fma_f32 v[184:185], v[48:49], v[48:49], v[184:185]
	v_add_f32_e32 v74, v75, v74
	v_add_f32_e32 v75, v181, v176
	v_mov_b32_e32 v186, v54
	v_mov_b32_e32 v187, v50
	v_mul_f32_e32 v188, v54, v54
	v_mul_f32_e32 v189, v51, v51
	v_add_f32_e32 v176, v182, v74
	v_add_f32_e32 v74, v184, v75
	v_pk_add_f32 v[190:191], v[54:55], v[50:51]
	v_pk_mul_f32 v[192:193], v[54:55], v[54:55]
	v_pk_fma_f32 v[186:187], v[186:187], v[186:187], v[188:189] op_sel_hi:[1,1,0]
	v_pk_add_f32 v[74:75], v[184:185], v[74:75] op_sel_hi:[1,0]
	v_mov_b32_e32 v191, v193
	v_mov_b32_e32 v186, v55
	v_add_f32_e32 v188, v183, v176
	v_mov_b32_e32 v74, v51
	v_pk_add_f32 v[176:177], v[190:191], v[188:189]
	v_pk_add_f32 v[74:75], v[186:187], v[74:75]
	s_nop 0
	v_pk_add_f32 v[74:75], v[176:177], v[74:75]
	ds_bpermute_b32 v176, v200, v74
	ds_bpermute_b32 v177, v200, v75
	s_waitcnt lgkmcnt(0)
	v_pk_add_f32 v[74:75], v[74:75], v[176:177]
	ds_bpermute_b32 v176, v203, v74
	ds_bpermute_b32 v177, v203, v75
	s_and_saveexec_b64 s[10:11], vcc
	s_cbranch_execz .LBB0_732
	v_lshl_add_u32 v178, v202, 5, s7
	s_waitcnt lgkmcnt(0)
	v_pk_add_f32 v[74:75], v[74:75], v[176:177]
	ds_write_b64 v178, v[74:75]
; DI float bflo(unsigned w) { return __uint_as_float(w << 16); }
; DI float bfhi(unsigned w) { return __uint_as_float(w & 0xffff0000u); }
;     DI void fused(pg8::f32x4 (&acc)[2][2][4][2], const pg8::Unit& u, int wr, int wc, int fr, int fq, pg8::PG8_LAS_T ldsp, int wid, int lane) const {
;     ...
; #pragma unroll
;         for (int ai = 0; ai < 2; ++ai)
; #pragma unroll
;             for (int m = 0; m < 4; ++m) {
;                 const int rt = ai * 128 + wr * 64 + m * 16 + fr, row = u.pm * 256 + rt;
;                 float sm = 0.f, sq = 0.f;
;                 float mu = 0.f, rs = 0.f;
;                 if (MODE == 0) { mu = stats[row * 2]; rs = stats[row * 2 + 1]; }
; #pragma unroll
;                 for (int bj = 0; bj < 2; ++bj) {
;                     const int col = u.pn * 256 + bj * 128 + wc * 32 + 8 * fq;
;                     const size_t idx = (size_t)row * DM + col;
;                     f32x4 v0, v1;
;                     if (MODE == 0) {
;                         const f32x4 x0 = *(const f32x4*)(x + idx), x1 = *(const f32x4*)(x + idx + 4);
;                         v0 = ((x0 - mu) * rs * gi[bj][0] + bi[bj][0]) * ALPHA + acc[ai][bj][m][0];
;                         v1 = ((x1 - mu) * rs * gi[bj][1] + bi[bj][1]) * ALPHA + acc[ai][bj][m][1];
;                     } else {
;                         const u32x4 w = *(const u32x4*)(pg + idx);
;                         const u32x4 hw = *(const u32x4*)(h1 + idx);
;                         v0 = (f32x4){bflo(hw.x), bfhi(hw.x), bflo(hw.y), bfhi(hw.y)} * ALPHA + acc[ai][bj][m][0];
;                         v1 = (f32x4){bflo(hw.z), bfhi(hw.z), bflo(hw.w), bfhi(hw.w)} * ALPHA + acc[ai][bj][m][1];
;                         v0[0] += bflo(w.x); v0[1] += bfhi(w.x); v0[2] += bflo(w.y); v0[3] += bfhi(w.y);
;                         v1[0] += bflo(w.z); v1[1] += bfhi(w.z); v1[2] += bflo(w.w); v1[3] += bfhi(w.w);
;                     }
;                     acc[ai][bj][m][0] = v0; acc[ai][bj][m][1] = v1;
; #pragma unroll
;                     for (int e = 0; e < 4; ++e) { sm += v0[e] + v1[e]; sq += v0[e] * v0[e] + v1[e] * v1[e]; }
;                 }
;                 sm += shx(sm, 16, lane); sm += shx(sm, 32, lane);
;                 sq += shx(sq, 16, lane); sq += shx(sq, 32, lane);
;                 if (fq == 0) { P[(rt * 4 + wc) * 2] = sm; P[(rt * 4 + wc) * 2 + 1] = sq; }
.LBB0_732:
	s_or_b64 exec, exec, s[10:11]
	v_add_u32_e32 v204, 0x90, v196
	v_add_u32_e32 v74, s5, v204
	s_waitcnt lgkmcnt(1)
	v_lshlrev_b32_e32 v176, 1, v74
	s_waitcnt lgkmcnt(0)
	v_ashrrev_i32_e32 v177, 31, v176
	v_lshl_add_u64 v[176:177], v[176:177], 2, s[0:1]
	v_ashrrev_i32_e32 v75, 31, v74
	v_readlane_b32 s12, v255, 1
	s_waitcnt vmcnt(5)
	v_mov_b64_e32 v[192:193], v[212:213]
	v_lshlrev_b64 v[176:177], 12, v[74:75]
	v_readlane_b32 s13, v255, 2
	v_readlane_b32 s14, v255, 3
	v_readlane_b32 s15, v255, 4
	v_lshl_add_u64 v[176:177], s[12:13], 0, v[176:177]
	v_lshl_add_u64 v[188:189], v[160:161], 2, v[176:177]
	v_mov_b64_e32 v[176:177], v[214:215]
	v_mov_b64_e32 v[178:179], v[216:217]
	v_mov_b64_e32 v[180:181], v[218:219]
	v_mov_b64_e32 v[182:183], v[220:221]
	v_mov_b64_e32 v[184:185], v[222:223]
	v_mov_b64_e32 v[186:187], v[224:225]
	s_nop 0
	v_mov_b64_e32 v[188:189], v[226:227]
	v_mov_b64_e32 v[190:191], v[228:229]
	global_load_dwordx2 v[212:213], v[248:249], off offset:1408
	s_mov_b64 s[56:57], 0xb0000
	v_lshl_add_u64 v[252:253], v[250:251], 0, s[56:57]
	global_load_dwordx4 v[214:217], v[252:253], off
	global_load_dwordx4 v[218:221], v[252:253], off offset:16
	global_load_dwordx4 v[222:225], v[252:253], off offset:512
	global_load_dwordx4 v[226:229], v[252:253], off offset:528
	v_readlane_b32 s16, v255, 5
	v_readlane_b32 s17, v255, 6
	v_readlane_b32 s18, v255, 7
	v_readlane_b32 s19, v255, 8
	v_readlane_b32 s20, v255, 9
	v_readlane_b32 s21, v255, 10
	v_readlane_b32 s22, v255, 11
	v_readlane_b32 s23, v255, 12
	v_readlane_b32 s24, v255, 13
	v_readlane_b32 s25, v255, 14
	v_readlane_b32 s26, v255, 15
	v_readlane_b32 s27, v255, 16
	v_sub_f32_e32 v177, v177, v192
	v_sub_f32_e32 v176, v176, v192
	v_sub_f32_e32 v181, v181, v192
	v_sub_f32_e32 v180, v180, v192
	v_sub_f32_e32 v179, v179, v192
	v_sub_f32_e32 v178, v178, v192
	v_sub_f32_e32 v183, v183, v192
	v_sub_f32_e32 v182, v182, v192
	v_pk_mul_f32 v[176:177], v[192:193], v[176:177] op_sel:[1,0]
	v_pk_mul_f32 v[180:181], v[192:193], v[180:181] op_sel:[1,0]
	v_pk_mul_f32 v[178:179], v[192:193], v[178:179] op_sel:[1,0]
	v_pk_mul_f32 v[182:183], v[192:193], v[182:183] op_sel:[1,0]
	v_pk_fma_f32 v[176:177], v[156:157], v[176:177], v[136:137]
	v_pk_fma_f32 v[180:181], v[140:141], v[180:181], v[152:153]
	v_sub_f32_e32 v185, v185, v192
	v_sub_f32_e32 v184, v184, v192
	v_pk_fma_f32 v[178:179], v[158:159], v[178:179], v[138:139]
	v_pk_fma_f32 v[182:183], v[142:143], v[182:183], v[154:155]
	v_pk_fma_f32 v[44:45], v[176:177], s[2:3], v[44:45] op_sel_hi:[1,0,1]
	v_pk_fma_f32 v[40:41], v[180:181], s[2:3], v[40:41] op_sel_hi:[1,0,1]
	v_sub_f32_e32 v187, v187, v192
	v_sub_f32_e32 v186, v186, v192
	v_sub_f32_e32 v189, v189, v192
	v_sub_f32_e32 v188, v188, v192
	v_pk_mul_f32 v[184:185], v[192:193], v[184:185] op_sel:[1,0]
	v_pk_fma_f32 v[46:47], v[178:179], s[2:3], v[46:47] op_sel_hi:[1,0,1]
	v_pk_fma_f32 v[42:43], v[182:183], s[2:3], v[42:43] op_sel_hi:[1,0,1]
	v_pk_add_f32 v[178:179], v[44:45], v[40:41]
	v_pk_mul_f32 v[180:181], v[40:41], v[40:41]
	v_sub_f32_e32 v191, v191, v192
	v_sub_f32_e32 v190, v190, v192
	v_pk_mul_f32 v[186:187], v[192:193], v[186:187] op_sel:[1,0]
	v_pk_mul_f32 v[188:189], v[192:193], v[188:189] op_sel:[1,0]
	v_pk_fma_f32 v[184:185], v[148:149], v[184:185], v[128:129]
	v_pk_mul_f32 v[182:183], v[42:43], v[42:43]
	v_add_f32_e32 v178, 0, v178
	v_pk_fma_f32 v[180:181], v[44:45], v[44:45], v[180:181]
	v_pk_mul_f32 v[190:191], v[192:193], v[190:191] op_sel:[1,0]
	v_pk_fma_f32 v[186:187], v[150:151], v[186:187], v[130:131]
	v_pk_fma_f32 v[188:189], v[132:133], v[188:189], v[144:145]
	v_pk_fma_f32 v[36:37], v[184:185], s[2:3], v[36:37] op_sel_hi:[1,0,1]
	v_pk_add_f32 v[176:177], v[46:47], v[42:43]
	v_pk_fma_f32 v[182:183], v[46:47], v[46:47], v[182:183]
	v_add_f32_e32 v178, v179, v178
	v_add_f32_e32 v179, v180, v181
	v_pk_fma_f32 v[190:191], v[134:135], v[190:191], v[146:147]
	v_pk_fma_f32 v[38:39], v[186:187], s[2:3], v[38:39] op_sel_hi:[1,0,1]
	v_pk_fma_f32 v[32:33], v[188:189], s[2:3], v[32:33] op_sel_hi:[1,0,1]
	v_pk_mul_f32 v[186:187], v[36:37], v[36:37]
	v_add_f32_e32 v176, v176, v178
	v_add_f32_e32 v178, v182, v179
	v_pk_fma_f32 v[34:35], v[190:191], s[2:3], v[34:35] op_sel_hi:[1,0,1]
	v_pk_add_f32 v[184:185], v[36:37], v[32:33]
	v_pk_fma_f32 v[186:187], v[32:33], v[32:33], v[186:187]
	v_add_f32_e32 v176, v177, v176
	v_add_f32_e32 v177, v183, v178
	v_mov_b32_e32 v188, v38
	v_mov_b32_e32 v189, v34
	v_mul_f32_e32 v190, v38, v38
	v_mul_f32_e32 v191, v35, v35
	v_add_f32_e32 v178, v184, v176
	v_add_f32_e32 v176, v186, v177
	v_pk_add_f32 v[192:193], v[38:39], v[34:35]
	v_pk_mul_f32 v[194:195], v[38:39], v[38:39]
	v_pk_fma_f32 v[188:189], v[188:189], v[188:189], v[190:191] op_sel_hi:[1,1,0]
	v_pk_add_f32 v[176:177], v[186:187], v[176:177] op_sel_hi:[1,0]
	v_mov_b32_e32 v193, v195
	v_mov_b32_e32 v188, v39
	v_add_f32_e32 v190, v185, v178
	v_mov_b32_e32 v176, v35
	v_pk_add_f32 v[178:179], v[192:193], v[190:191]
	v_pk_add_f32 v[176:177], v[188:189], v[176:177]
	s_nop 0
	v_pk_add_f32 v[176:177], v[178:179], v[176:177]
	ds_bpermute_b32 v178, v200, v176
	ds_bpermute_b32 v179, v200, v177
	s_waitcnt lgkmcnt(0)
	v_pk_add_f32 v[176:177], v[176:177], v[178:179]
	ds_bpermute_b32 v178, v203, v176
	ds_bpermute_b32 v179, v203, v177
	s_and_saveexec_b64 s[2:3], vcc
	s_cbranch_execz .LBB0_734
	v_lshl_add_u32 v180, v204, 5, s7
	s_waitcnt lgkmcnt(0)
	v_pk_add_f32 v[176:177], v[176:177], v[178:179]
	ds_write_b64 v180, v[176:177]
; DI float bflo(unsigned w) { return __uint_as_float(w << 16); }
; DI float bfhi(unsigned w) { return __uint_as_float(w & 0xffff0000u); }
;     DI void fused(pg8::f32x4 (&acc)[2][2][4][2], const pg8::Unit& u, int wr, int wc, int fr, int fq, pg8::PG8_LAS_T ldsp, int wid, int lane) const {
;     ...
; #pragma unroll
;         for (int ai = 0; ai < 2; ++ai)
; #pragma unroll
;             for (int m = 0; m < 4; ++m) {
;                 const int rt = ai * 128 + wr * 64 + m * 16 + fr, row = u.pm * 256 + rt;
;                 float sm = 0.f, sq = 0.f;
;                 float mu = 0.f, rs = 0.f;
;                 if (MODE == 0) { mu = stats[row * 2]; rs = stats[row * 2 + 1]; }
; #pragma unroll
;                 for (int bj = 0; bj < 2; ++bj) {
;                     const int col = u.pn * 256 + bj * 128 + wc * 32 + 8 * fq;
;                     const size_t idx = (size_t)row * DM + col;
;                     f32x4 v0, v1;
;                     if (MODE == 0) {
;                         const f32x4 x0 = *(const f32x4*)(x + idx), x1 = *(const f32x4*)(x + idx + 4);
;                         v0 = ((x0 - mu) * rs * gi[bj][0] + bi[bj][0]) * ALPHA + acc[ai][bj][m][0];
;                         v1 = ((x1 - mu) * rs * gi[bj][1] + bi[bj][1]) * ALPHA + acc[ai][bj][m][1];
;                     } else {
;                         const u32x4 w = *(const u32x4*)(pg + idx);
;                         const u32x4 hw = *(const u32x4*)(h1 + idx);
;                         v0 = (f32x4){bflo(hw.x), bfhi(hw.x), bflo(hw.y), bfhi(hw.y)} * ALPHA + acc[ai][bj][m][0];
;                         v1 = (f32x4){bflo(hw.z), bfhi(hw.z), bflo(hw.w), bfhi(hw.w)} * ALPHA + acc[ai][bj][m][1];
;                         v0[0] += bflo(w.x); v0[1] += bfhi(w.x); v0[2] += bflo(w.y); v0[3] += bfhi(w.y);
;                         v1[0] += bflo(w.z); v1[1] += bfhi(w.z); v1[2] += bflo(w.w); v1[3] += bfhi(w.w);
;                     }
;                     acc[ai][bj][m][0] = v0; acc[ai][bj][m][1] = v1;
; #pragma unroll
;                     for (int e = 0; e < 4; ++e) { sm += v0[e] + v1[e]; sq += v0[e] * v0[e] + v1[e] * v1[e]; }
;                 }
;                 sm += shx(sm, 16, lane); sm += shx(sm, 32, lane);
;                 sq += shx(sq, 16, lane); sq += shx(sq, 32, lane);
;                 if (fq == 0) { P[(rt * 4 + wc) * 2] = sm; P[(rt * 4 + wc) * 2 + 1] = sq; }
.LBB0_734:
	s_or_b64 exec, exec, s[2:3]
	v_add_u32_e32 v205, 0xa0, v196
	v_add_u32_e32 v176, s5, v205
	s_waitcnt lgkmcnt(1)
	v_lshlrev_b32_e32 v178, 1, v176
	s_waitcnt lgkmcnt(0)
	v_ashrrev_i32_e32 v179, 31, v178
	v_lshl_add_u64 v[178:179], v[178:179], 2, s[0:1]
	v_ashrrev_i32_e32 v177, 31, v176
	v_readlane_b32 s12, v255, 1
	s_waitcnt vmcnt(5)
	v_mov_b64_e32 v[194:195], v[230:231]
	v_lshlrev_b64 v[178:179], 12, v[176:177]
	v_readlane_b32 s13, v255, 2
	s_mov_b32 s2, 0x3f9837f0
	v_readlane_b32 s14, v255, 3
	v_lshl_add_u64 v[178:179], s[12:13], 0, v[178:179]
	v_lshl_add_u64 v[190:191], v[160:161], 2, v[178:179]
	v_mov_b64_e32 v[178:179], v[232:233]
	v_mov_b64_e32 v[180:181], v[234:235]
	v_mov_b64_e32 v[182:183], v[236:237]
	v_mov_b64_e32 v[184:185], v[238:239]
	v_mov_b64_e32 v[186:187], v[240:241]
	v_mov_b64_e32 v[188:189], v[242:243]
	s_nop 0
	v_mov_b64_e32 v[190:191], v[244:245]
	v_mov_b64_e32 v[192:193], v[246:247]
	v_readlane_b32 s15, v255, 4
	v_readlane_b32 s16, v255, 5
	v_readlane_b32 s17, v255, 6
	v_readlane_b32 s18, v255, 7
	v_readlane_b32 s19, v255, 8
	v_readlane_b32 s20, v255, 9
	v_readlane_b32 s21, v255, 10
	v_readlane_b32 s22, v255, 11
	v_readlane_b32 s23, v255, 12
	v_readlane_b32 s24, v255, 13
	v_readlane_b32 s25, v255, 14
	v_readlane_b32 s26, v255, 15
	v_readlane_b32 s27, v255, 16
	v_sub_f32_e32 v179, v179, v194
	v_sub_f32_e32 v178, v178, v194
	v_sub_f32_e32 v183, v183, v194
	v_sub_f32_e32 v182, v182, v194
	v_sub_f32_e32 v185, v185, v194
	v_sub_f32_e32 v184, v184, v194
	v_sub_f32_e32 v187, v187, v194
	v_sub_f32_e32 v186, v186, v194
	v_sub_f32_e32 v191, v191, v194
	v_sub_f32_e32 v190, v190, v194
	v_sub_f32_e32 v193, v193, v194
	v_sub_f32_e32 v192, v192, v194
	v_pk_mul_f32 v[178:179], v[194:195], v[178:179] op_sel:[1,0]
	v_pk_mul_f32 v[182:183], v[194:195], v[182:183] op_sel:[1,0]
	v_sub_f32_e32 v181, v181, v194
	v_sub_f32_e32 v180, v180, v194
	v_sub_f32_e32 v189, v189, v194
	v_sub_f32_e32 v188, v188, v194
	v_pk_mul_f32 v[184:185], v[194:195], v[184:185] op_sel:[1,0]
	v_pk_mul_f32 v[186:187], v[194:195], v[186:187] op_sel:[1,0]
	v_pk_mul_f32 v[192:193], v[194:195], v[192:193] op_sel:[1,0]
	v_pk_mul_f32 v[190:191], v[194:195], v[190:191] op_sel:[1,0]
	v_pk_fma_f32 v[178:179], v[156:157], v[178:179], v[136:137]
	v_pk_fma_f32 v[182:183], v[140:141], v[182:183], v[152:153]
	v_pk_mul_f32 v[180:181], v[194:195], v[180:181] op_sel:[1,0]
	v_pk_mul_f32 v[188:189], v[194:195], v[188:189] op_sel:[1,0]
	v_pk_fma_f32 v[184:185], v[142:143], v[184:185], v[154:155]
	v_pk_fma_f32 v[194:195], v[148:149], v[186:187], v[128:129]
	v_pk_fma_f32 v[208:209], v[132:133], v[190:191], v[144:145]
	v_pk_fma_f32 v[210:211], v[134:135], v[192:193], v[146:147]
	v_pk_fma_f32 v[190:191], v[178:179], s[2:3], v[28:29] op_sel_hi:[1,0,1]
	v_pk_fma_f32 v[186:187], v[182:183], s[2:3], v[24:25] op_sel_hi:[1,0,1]
	v_pk_fma_f32 v[180:181], v[158:159], v[180:181], v[138:139]
	v_pk_fma_f32 v[206:207], v[150:151], v[188:189], v[130:131]
	v_pk_fma_f32 v[188:189], v[184:185], s[2:3], v[26:27] op_sel_hi:[1,0,1]
	v_pk_fma_f32 v[182:183], v[194:195], s[2:3], v[20:21] op_sel_hi:[1,0,1]
	v_pk_fma_f32 v[178:179], v[210:211], s[2:3], v[18:19] op_sel_hi:[1,0,1]
	v_pk_add_f32 v[18:19], v[190:191], v[186:187]
	v_pk_mul_f32 v[20:21], v[186:187], v[186:187]
	v_pk_fma_f32 v[192:193], v[180:181], s[2:3], v[30:31] op_sel_hi:[1,0,1]
	v_pk_fma_f32 v[184:185], v[206:207], s[2:3], v[22:23] op_sel_hi:[1,0,1]
	v_pk_mul_f32 v[22:23], v[188:189], v[188:189]
	v_add_f32_e32 v18, 0, v18
	v_pk_fma_f32 v[20:21], v[190:191], v[190:191], v[20:21]
	v_pk_fma_f32 v[180:181], v[208:209], s[2:3], v[16:17] op_sel_hi:[1,0,1]
	v_pk_add_f32 v[16:17], v[192:193], v[188:189]
	v_pk_fma_f32 v[22:23], v[192:193], v[192:193], v[22:23]
	v_add_f32_e32 v18, v19, v18
	v_add_f32_e32 v19, v20, v21
	v_pk_mul_f32 v[26:27], v[182:183], v[182:183]
	v_add_f32_e32 v16, v16, v18
	v_add_f32_e32 v18, v22, v19
	v_pk_add_f32 v[24:25], v[182:183], v[180:181]
	v_pk_fma_f32 v[26:27], v[180:181], v[180:181], v[26:27]
	v_add_f32_e32 v16, v17, v16
	v_add_f32_e32 v17, v23, v18
	v_mov_b32_e32 v28, v184
	v_mov_b32_e32 v29, v178
	v_mul_f32_e32 v30, v184, v184
	v_mul_f32_e32 v31, v179, v179
	v_add_f32_e32 v18, v24, v16
	v_add_f32_e32 v16, v26, v17
	v_pk_add_f32 v[194:195], v[184:185], v[178:179]
	v_pk_mul_f32 v[206:207], v[184:185], v[184:185]
	v_pk_fma_f32 v[28:29], v[28:29], v[28:29], v[30:31] op_sel_hi:[1,1,0]
	v_pk_add_f32 v[16:17], v[26:27], v[16:17] op_sel_hi:[1,0]
	v_mov_b32_e32 v195, v207
	v_mov_b32_e32 v28, v185
	v_add_f32_e32 v30, v25, v18
	v_mov_b32_e32 v16, v179
	v_pk_add_f32 v[18:19], v[194:195], v[30:31]
	v_pk_add_f32 v[16:17], v[28:29], v[16:17]
	s_nop 0
	v_pk_add_f32 v[16:17], v[18:19], v[16:17]
	ds_bpermute_b32 v18, v200, v16
	ds_bpermute_b32 v19, v200, v17
	s_waitcnt lgkmcnt(0)
	v_pk_add_f32 v[16:17], v[16:17], v[18:19]
	ds_bpermute_b32 v18, v203, v16
	ds_bpermute_b32 v19, v203, v17
	s_and_saveexec_b64 s[10:11], vcc
	s_cbranch_execz .LBB0_736
	v_lshl_add_u32 v20, v205, 5, s7
	s_waitcnt lgkmcnt(0)
	v_pk_add_f32 v[16:17], v[16:17], v[18:19]
	ds_write_b64 v20, v[16:17]
; DI float bflo(unsigned w) { return __uint_as_float(w << 16); }
; DI float bfhi(unsigned w) { return __uint_as_float(w & 0xffff0000u); }
;     DI void fused(pg8::f32x4 (&acc)[2][2][4][2], const pg8::Unit& u, int wr, int wc, int fr, int fq, pg8::PG8_LAS_T ldsp, int wid, int lane) const {
;     ...
; #pragma unroll
;         for (int ai = 0; ai < 2; ++ai)
; #pragma unroll
;             for (int m = 0; m < 4; ++m) {
;                 const int rt = ai * 128 + wr * 64 + m * 16 + fr, row = u.pm * 256 + rt;
;                 float sm = 0.f, sq = 0.f;
;                 float mu = 0.f, rs = 0.f;
;                 if (MODE == 0) { mu = stats[row * 2]; rs = stats[row * 2 + 1]; }
; #pragma unroll
;                 for (int bj = 0; bj < 2; ++bj) {
;                     const int col = u.pn * 256 + bj * 128 + wc * 32 + 8 * fq;
;                     const size_t idx = (size_t)row * DM + col;
;                     f32x4 v0, v1;
;                     if (MODE == 0) {
;                         const f32x4 x0 = *(const f32x4*)(x + idx), x1 = *(const f32x4*)(x + idx + 4);
;                         v0 = ((x0 - mu) * rs * gi[bj][0] + bi[bj][0]) * ALPHA + acc[ai][bj][m][0];
;                         v1 = ((x1 - mu) * rs * gi[bj][1] + bi[bj][1]) * ALPHA + acc[ai][bj][m][1];
;                     } else {
;                         const u32x4 w = *(const u32x4*)(pg + idx);
;                         const u32x4 hw = *(const u32x4*)(h1 + idx);
;                         v0 = (f32x4){bflo(hw.x), bfhi(hw.x), bflo(hw.y), bfhi(hw.y)} * ALPHA + acc[ai][bj][m][0];
;                         v1 = (f32x4){bflo(hw.z), bfhi(hw.z), bflo(hw.w), bfhi(hw.w)} * ALPHA + acc[ai][bj][m][1];
;                         v0[0] += bflo(w.x); v0[1] += bfhi(w.x); v0[2] += bflo(w.y); v0[3] += bfhi(w.y);
;                         v1[0] += bflo(w.z); v1[1] += bfhi(w.z); v1[2] += bflo(w.w); v1[3] += bfhi(w.w);
;                     }
;                     acc[ai][bj][m][0] = v0; acc[ai][bj][m][1] = v1;
; #pragma unroll
;                     for (int e = 0; e < 4; ++e) { sm += v0[e] + v1[e]; sq += v0[e] * v0[e] + v1[e] * v1[e]; }
;                 }
;                 sm += shx(sm, 16, lane); sm += shx(sm, 32, lane);
;                 sq += shx(sq, 16, lane); sq += shx(sq, 32, lane);
;                 if (fq == 0) { P[(rt * 4 + wc) * 2] = sm; P[(rt * 4 + wc) * 2 + 1] = sq; }
.LBB0_736:
	s_or_b64 exec, exec, s[10:11]
	v_add_u32_e32 v206, 0xb0, v196
	v_add_u32_e32 v194, s5, v206
	v_lshlrev_b32_e32 v16, 1, v194
	v_ashrrev_i32_e32 v17, 31, v16
	v_lshl_add_u64 v[16:17], v[16:17], 2, s[0:1]
	v_ashrrev_i32_e32 v195, 31, v194
	v_readlane_b32 s12, v255, 1
	s_waitcnt vmcnt(0)
	v_mov_b64_e32 v[208:209], v[212:213]
	v_lshlrev_b64 v[16:17], 12, v[194:195]
	v_readlane_b32 s13, v255, 2
	v_readlane_b32 s14, v255, 3
	v_readlane_b32 s15, v255, 4
	v_lshl_add_u64 v[16:17], s[12:13], 0, v[16:17]
	v_lshl_add_u64 v[28:29], v[160:161], 2, v[16:17]
	s_waitcnt lgkmcnt(0)
	v_mov_b64_e32 v[16:17], v[214:215]
	v_mov_b64_e32 v[18:19], v[216:217]
	v_mov_b64_e32 v[20:21], v[218:219]
	v_mov_b64_e32 v[22:23], v[220:221]
	v_mov_b64_e32 v[24:25], v[222:223]
	v_mov_b64_e32 v[26:27], v[224:225]
	s_nop 0
	v_mov_b64_e32 v[28:29], v[226:227]
	v_mov_b64_e32 v[30:31], v[228:229]
	v_readlane_b32 s16, v255, 5
	v_readlane_b32 s17, v255, 6
	v_readlane_b32 s18, v255, 7
	v_readlane_b32 s19, v255, 8
	v_readlane_b32 s20, v255, 9
	v_readlane_b32 s21, v255, 10
	v_readlane_b32 s22, v255, 11
	v_readlane_b32 s23, v255, 12
	v_readlane_b32 s24, v255, 13
	v_readlane_b32 s25, v255, 14
	v_readlane_b32 s26, v255, 15
	v_readlane_b32 s27, v255, 16
	v_sub_f32_e32 v17, v17, v208
	v_sub_f32_e32 v16, v16, v208
	v_sub_f32_e32 v21, v21, v208
	v_sub_f32_e32 v20, v20, v208
	v_sub_f32_e32 v23, v23, v208
	v_sub_f32_e32 v22, v22, v208
	v_sub_f32_e32 v25, v25, v208
	v_sub_f32_e32 v24, v24, v208
	v_sub_f32_e32 v31, v31, v208
	v_sub_f32_e32 v30, v30, v208
	v_pk_mul_f32 v[16:17], v[208:209], v[16:17] op_sel:[1,0]
	v_pk_mul_f32 v[20:21], v[208:209], v[20:21] op_sel:[1,0]
	v_sub_f32_e32 v19, v19, v208
	v_sub_f32_e32 v18, v18, v208
	v_sub_f32_e32 v27, v27, v208
	v_sub_f32_e32 v26, v26, v208
	v_sub_f32_e32 v29, v29, v208
	v_sub_f32_e32 v28, v28, v208
	v_pk_mul_f32 v[22:23], v[208:209], v[22:23] op_sel:[1,0]
	v_pk_mul_f32 v[24:25], v[208:209], v[24:25] op_sel:[1,0]
	v_pk_mul_f32 v[30:31], v[208:209], v[30:31] op_sel:[1,0]
	v_pk_fma_f32 v[16:17], v[156:157], v[16:17], v[136:137]
	v_pk_fma_f32 v[20:21], v[140:141], v[20:21], v[152:153]
	v_pk_mul_f32 v[18:19], v[208:209], v[18:19] op_sel:[1,0]
	v_pk_mul_f32 v[26:27], v[208:209], v[26:27] op_sel:[1,0]
	v_pk_mul_f32 v[28:29], v[208:209], v[28:29] op_sel:[1,0]
	v_pk_fma_f32 v[22:23], v[142:143], v[22:23], v[154:155]
	v_pk_fma_f32 v[24:25], v[148:149], v[24:25], v[128:129]
	v_pk_fma_f32 v[30:31], v[134:135], v[30:31], v[146:147]
	v_pk_fma_f32 v[140:141], v[16:17], s[2:3], v[12:13] op_sel_hi:[1,0,1]
	v_pk_fma_f32 v[136:137], v[20:21], s[2:3], v[8:9] op_sel_hi:[1,0,1]
	v_pk_fma_f32 v[18:19], v[158:159], v[18:19], v[138:139]
	v_pk_fma_f32 v[26:27], v[150:151], v[26:27], v[130:131]
	v_pk_fma_f32 v[28:29], v[132:133], v[28:29], v[144:145]
	v_pk_fma_f32 v[138:139], v[22:23], s[2:3], v[10:11] op_sel_hi:[1,0,1]
	v_pk_fma_f32 v[132:133], v[24:25], s[2:3], v[4:5] op_sel_hi:[1,0,1]
	v_pk_fma_f32 v[128:129], v[30:31], s[2:3], v[2:3] op_sel_hi:[1,0,1]
	v_pk_add_f32 v[2:3], v[140:141], v[136:137]
	v_pk_mul_f32 v[4:5], v[136:137], v[136:137]
	v_pk_fma_f32 v[142:143], v[18:19], s[2:3], v[14:15] op_sel_hi:[1,0,1]
	v_pk_fma_f32 v[134:135], v[26:27], s[2:3], v[6:7] op_sel_hi:[1,0,1]
	v_pk_mul_f32 v[6:7], v[138:139], v[138:139]
	v_add_f32_e32 v2, 0, v2
	v_pk_fma_f32 v[4:5], v[140:141], v[140:141], v[4:5]
	v_pk_fma_f32 v[130:131], v[28:29], s[2:3], v[0:1] op_sel_hi:[1,0,1]
	v_pk_add_f32 v[0:1], v[142:143], v[138:139]
	v_pk_fma_f32 v[6:7], v[142:143], v[142:143], v[6:7]
	v_add_f32_e32 v2, v3, v2
	v_add_f32_e32 v3, v4, v5
	v_pk_mul_f32 v[10:11], v[132:133], v[132:133]
	v_add_f32_e32 v0, v0, v2
	v_add_f32_e32 v2, v6, v3
	v_pk_add_f32 v[8:9], v[132:133], v[130:131]
	v_pk_fma_f32 v[10:11], v[130:131], v[130:131], v[10:11]
	v_add_f32_e32 v0, v1, v0
	v_add_f32_e32 v1, v7, v2
	v_mov_b32_e32 v12, v134
	v_mov_b32_e32 v13, v128
	v_mul_f32_e32 v14, v134, v134
	v_mul_f32_e32 v15, v129, v129
	v_add_f32_e32 v2, v8, v0
	v_add_f32_e32 v0, v10, v1
	v_pk_add_f32 v[16:17], v[134:135], v[128:129]
	v_pk_mul_f32 v[18:19], v[134:135], v[134:135]
	v_pk_fma_f32 v[12:13], v[12:13], v[12:13], v[14:15] op_sel_hi:[1,1,0]
	v_pk_add_f32 v[0:1], v[10:11], v[0:1] op_sel_hi:[1,0]
	v_mov_b32_e32 v17, v19
	v_mov_b32_e32 v12, v135
	v_add_f32_e32 v14, v9, v2
	v_mov_b32_e32 v0, v129
	v_pk_add_f32 v[2:3], v[16:17], v[14:15]
	v_pk_add_f32 v[0:1], v[12:13], v[0:1]
	s_nop 0
	v_pk_add_f32 v[0:1], v[2:3], v[0:1]
	ds_bpermute_b32 v2, v200, v0
	ds_bpermute_b32 v3, v200, v1
	s_waitcnt lgkmcnt(0)
	v_pk_add_f32 v[0:1], v[0:1], v[2:3]
	ds_bpermute_b32 v2, v203, v0
	ds_bpermute_b32 v3, v203, v1
	s_and_saveexec_b64 s[0:1], vcc
	s_cbranch_execz .LBB0_738
	v_lshl_add_u32 v4, v206, 5, s7
	s_waitcnt lgkmcnt(0)
	v_pk_add_f32 v[0:1], v[0:1], v[2:3]
	ds_write_b64 v4, v[0:1]
